# nt hint on the once-read x loads (P0) and on the final output stores; on top of v28
# speedup vs baseline: 1.0018x; 1.0018x over previous
; __device__ __forceinline__ float bflo(unsigned w) { return __uint_as_float(w << 16); }
; __device__ __forceinline__ float bfhi(unsigned w) { return __uint_as_float(w & 0xffff0000u); }
; __device__ __forceinline__ float row_rstd(const float* ss, int row) {
;     const f32x4* q = (const f32x4*)(ss + (size_t)row * 16); const f32x4 s4 = (q[0] + q[1]) + (q[2] + q[3]);
;     return rsqrtf(((s4[0] + s4[1]) + (s4[2] + s4[3])) * (1.0f / D) + EPS);
; }
; __global__ void __launch_bounds__(512, 2) fwd_mega(Args a) {
;     ...
;         for (int row = gw; row < M; row += NGW) {
;             const float rs = row_rstd(ssf, row);
;             f32x4* orow = (f32x4*)(a.out + (size_t)row * D) + lane; const u32x2* xr = (const u32x2*)(XB + (size_t)row * D) + lane;
; #pragma unroll
;             for (int j = 0; j < 4; ++j) { const u32x2 w = xr[64 * j]; orow[64 * j] = (f32x4){bflo(w.x), bfhi(w.x), bflo(w.y), bfhi(w.y)} * rs * gv[j]; }
;         }
.Lfn_loop:
	s_mov_b32 s20, s0
	s_lshl_b32 s12, s20, 6
	s_add_u32 s12, s64, s12
	s_addc_u32 s13, s65, 0
	s_add_u32 s12, s12, 0x18680000
	s_addc_u32 s13, s13, 0
	global_load_dwordx4 v[48:51], v17, s[12:13]
	global_load_dwordx4 v[52:55], v17, s[12:13] offset:16
	global_load_dwordx4 v[56:59], v17, s[12:13] offset:32
	global_load_dwordx4 v[60:63], v17, s[12:13] offset:48
	s_lshl_b32 s14, s20, 11
	s_add_u32 s14, s64, s14
	s_addc_u32 s15, s65, 0
	s_add_u32 s14, s14, 0x6280000
	s_addc_u32 s15, s15, 0
	global_load_dwordx2 v[64:65], v40, s[14:15]
	global_load_dwordx2 v[66:67], v40, s[14:15] offset:512
	global_load_dwordx2 v[68:69], v40, s[14:15] offset:1024
	global_load_dwordx2 v[70:71], v40, s[14:15] offset:1536
	s_mul_i32 s21, s16, 1
	s_add_i32 s21, s21, s0
	s_cmp_gt_i32 s21, 0x3fff
	s_cselect_b32 s21, s0, s21
	s_lshl_b32 s12, s21, 6
	s_add_u32 s12, s64, s12
	s_addc_u32 s13, s65, 0
	s_add_u32 s12, s12, 0x18680000
	s_addc_u32 s13, s13, 0
	global_load_dwordx4 v[72:75], v17, s[12:13]
	global_load_dwordx4 v[76:79], v17, s[12:13] offset:16
	global_load_dwordx4 v[80:83], v17, s[12:13] offset:32
	global_load_dwordx4 v[84:87], v17, s[12:13] offset:48
	s_lshl_b32 s14, s21, 11
	s_add_u32 s14, s64, s14
	s_addc_u32 s15, s65, 0
	s_add_u32 s14, s14, 0x6280000
	s_addc_u32 s15, s15, 0
	global_load_dwordx2 v[88:89], v40, s[14:15]
	global_load_dwordx2 v[90:91], v40, s[14:15] offset:512
	global_load_dwordx2 v[92:93], v40, s[14:15] offset:1024
	global_load_dwordx2 v[94:95], v40, s[14:15] offset:1536
	s_mul_i32 s22, s16, 2
	s_add_i32 s22, s22, s0
	s_cmp_gt_i32 s22, 0x3fff
	s_cselect_b32 s22, s0, s22
	s_lshl_b32 s12, s22, 6
	s_add_u32 s12, s64, s12
	s_addc_u32 s13, s65, 0
	s_add_u32 s12, s12, 0x18680000
	s_addc_u32 s13, s13, 0
	global_load_dwordx4 v[96:99], v17, s[12:13]
	global_load_dwordx4 v[100:103], v17, s[12:13] offset:16
	global_load_dwordx4 v[104:107], v17, s[12:13] offset:32
	global_load_dwordx4 v[108:111], v17, s[12:13] offset:48
	s_lshl_b32 s14, s22, 11
	s_add_u32 s14, s64, s14
	s_addc_u32 s15, s65, 0
	s_add_u32 s14, s14, 0x6280000
	s_addc_u32 s15, s15, 0
	global_load_dwordx2 v[112:113], v40, s[14:15]
	global_load_dwordx2 v[114:115], v40, s[14:15] offset:512
	global_load_dwordx2 v[116:117], v40, s[14:15] offset:1024
	global_load_dwordx2 v[118:119], v40, s[14:15] offset:1536
	s_mul_i32 s23, s16, 3
	s_add_i32 s23, s23, s0
	s_cmp_gt_i32 s23, 0x3fff
	s_cselect_b32 s23, s0, s23
	s_lshl_b32 s12, s23, 6
	s_add_u32 s12, s64, s12
	s_addc_u32 s13, s65, 0
	s_add_u32 s12, s12, 0x18680000
	s_addc_u32 s13, s13, 0
	global_load_dwordx4 v[120:123], v17, s[12:13]
	global_load_dwordx4 v[124:127], v17, s[12:13] offset:16
	global_load_dwordx4 v[128:131], v17, s[12:13] offset:32
	global_load_dwordx4 v[132:135], v17, s[12:13] offset:48
	s_lshl_b32 s14, s23, 11
	s_add_u32 s14, s64, s14
	s_addc_u32 s15, s65, 0
	s_add_u32 s14, s14, 0x6280000
	s_addc_u32 s15, s15, 0
	global_load_dwordx2 v[136:137], v40, s[14:15]
	global_load_dwordx2 v[138:139], v40, s[14:15] offset:512
	global_load_dwordx2 v[140:141], v40, s[14:15] offset:1024
	global_load_dwordx2 v[142:143], v40, s[14:15] offset:1536
	s_mov_b32 s1, 0x800000
	s_waitcnt vmcnt(24)
	v_pk_add_f32 v[48:49], v[48:49], v[52:53]
	v_pk_add_f32 v[50:51], v[50:51], v[54:55]
	v_pk_add_f32 v[56:57], v[56:57], v[60:61]
	v_pk_add_f32 v[58:59], v[58:59], v[62:63]
	v_pk_add_f32 v[48:49], v[48:49], v[56:57]
	v_pk_add_f32 v[50:51], v[50:51], v[58:59]
	v_add_f32_e32 v48, v48, v49
	v_add_f32_e32 v50, v50, v51
	v_add_f32_e32 v48, v48, v50
	v_fmamk_f32 v48, v48, 0x3a800000, v22
	v_mul_f32_e32 v49, 0x4b800000, v48
	v_cmp_gt_f32_e32 vcc, s1, v48
	s_nop 1
	v_cndmask_b32_e32 v48, v48, v49, vcc
	v_rsq_f32_e32 v48, v48
	s_nop 0
	v_mul_f32_e32 v49, 0x45800000, v48
	v_cndmask_b32_e32 v52, v48, v49, vcc
	s_lshl_b32 s14, s20, 12
	s_add_u32 s14, s50, s14
	s_addc_u32 s15, s51, 0
	v_lshlrev_b32_e32 v48, 16, v64
	v_and_b32_e32 v49, 0xffff0000, v64
	v_lshlrev_b32_e32 v50, 16, v65
	v_and_b32_e32 v51, 0xffff0000, v65
	v_pk_mul_f32 v[48:49], v[52:53], v[48:49] op_sel_hi:[0,1]
	v_pk_mul_f32 v[50:51], v[52:53], v[50:51] op_sel_hi:[0,1]
	v_pk_mul_f32 v[56:57], v[0:1], v[48:49]
	v_pk_mul_f32 v[58:59], v[2:3], v[50:51]
	global_store_dwordx4 v41, v[56:59], s[14:15] nt
	v_lshlrev_b32_e32 v48, 16, v66
	v_and_b32_e32 v49, 0xffff0000, v66
	v_lshlrev_b32_e32 v50, 16, v67
	v_and_b32_e32 v51, 0xffff0000, v67
	v_pk_mul_f32 v[48:49], v[52:53], v[48:49] op_sel_hi:[0,1]
	v_pk_mul_f32 v[50:51], v[52:53], v[50:51] op_sel_hi:[0,1]
	v_pk_mul_f32 v[60:61], v[4:5], v[48:49]
	v_pk_mul_f32 v[62:63], v[6:7], v[50:51]
	global_store_dwordx4 v41, v[60:63], s[14:15] offset:1024 nt
	s_nop 0
	v_lshlrev_b32_e32 v48, 16, v68
	v_and_b32_e32 v49, 0xffff0000, v68
	v_lshlrev_b32_e32 v50, 16, v69
	v_and_b32_e32 v51, 0xffff0000, v69
	v_pk_mul_f32 v[48:49], v[52:53], v[48:49] op_sel_hi:[0,1]
	v_pk_mul_f32 v[50:51], v[52:53], v[50:51] op_sel_hi:[0,1]
	v_pk_mul_f32 v[56:57], v[8:9], v[48:49]
	v_pk_mul_f32 v[58:59], v[10:11], v[50:51]
	global_store_dwordx4 v41, v[56:59], s[14:15] offset:2048 nt
	s_nop 0
	v_lshlrev_b32_e32 v48, 16, v70
	v_and_b32_e32 v49, 0xffff0000, v70
	v_lshlrev_b32_e32 v50, 16, v71
	v_and_b32_e32 v51, 0xffff0000, v71
	v_pk_mul_f32 v[48:49], v[52:53], v[48:49] op_sel_hi:[0,1]
	v_pk_mul_f32 v[50:51], v[52:53], v[50:51] op_sel_hi:[0,1]
	v_pk_mul_f32 v[60:61], v[12:13], v[48:49]
	v_pk_mul_f32 v[62:63], v[14:15], v[50:51]
	global_store_dwordx4 v41, v[60:63], s[14:15] offset:3072 nt
	s_nop 0
	s_waitcnt vmcnt(20)
; __device__ __forceinline__ float bflo(unsigned w) { return __uint_as_float(w << 16); }
; __device__ __forceinline__ float bfhi(unsigned w) { return __uint_as_float(w & 0xffff0000u); }
; __device__ __forceinline__ float row_rstd(const float* ss, int row) {
;     const f32x4* q = (const f32x4*)(ss + (size_t)row * 16); const f32x4 s4 = (q[0] + q[1]) + (q[2] + q[3]);
;     return rsqrtf(((s4[0] + s4[1]) + (s4[2] + s4[3])) * (1.0f / D) + EPS);
; }
; __global__ void __launch_bounds__(512, 2) fwd_mega(Args a) {
;     ...
;         for (int row = gw; row < M; row += NGW) {
;             const float rs = row_rstd(ssf, row);
;             f32x4* orow = (f32x4*)(a.out + (size_t)row * D) + lane; const u32x2* xr = (const u32x2*)(XB + (size_t)row * D) + lane;
; #pragma unroll
;             for (int j = 0; j < 4; ++j) { const u32x2 w = xr[64 * j]; orow[64 * j] = (f32x4){bflo(w.x), bfhi(w.x), bflo(w.y), bfhi(w.y)} * rs * gv[j]; }
;         }
	v_pk_add_f32 v[72:73], v[72:73], v[76:77]
	v_pk_add_f32 v[74:75], v[74:75], v[78:79]
	v_pk_add_f32 v[80:81], v[80:81], v[84:85]
	v_pk_add_f32 v[82:83], v[82:83], v[86:87]
	v_pk_add_f32 v[72:73], v[72:73], v[80:81]
	v_pk_add_f32 v[74:75], v[74:75], v[82:83]
	v_add_f32_e32 v72, v72, v73
	v_add_f32_e32 v74, v74, v75
	v_add_f32_e32 v72, v72, v74
	v_fmamk_f32 v72, v72, 0x3a800000, v22
	v_mul_f32_e32 v73, 0x4b800000, v72
	v_cmp_gt_f32_e32 vcc, s1, v72
	s_nop 1
	v_cndmask_b32_e32 v72, v72, v73, vcc
	v_rsq_f32_e32 v72, v72
	s_nop 0
	v_mul_f32_e32 v73, 0x45800000, v72
	v_cndmask_b32_e32 v76, v72, v73, vcc
	s_lshl_b32 s14, s21, 12
	s_add_u32 s14, s50, s14
	s_addc_u32 s15, s51, 0
	v_lshlrev_b32_e32 v72, 16, v88
	v_and_b32_e32 v73, 0xffff0000, v88
	v_lshlrev_b32_e32 v74, 16, v89
	v_and_b32_e32 v75, 0xffff0000, v89
	v_pk_mul_f32 v[72:73], v[76:77], v[72:73] op_sel_hi:[0,1]
	v_pk_mul_f32 v[74:75], v[76:77], v[74:75] op_sel_hi:[0,1]
	v_pk_mul_f32 v[80:81], v[0:1], v[72:73]
	v_pk_mul_f32 v[82:83], v[2:3], v[74:75]
	global_store_dwordx4 v41, v[80:83], s[14:15] nt
	v_lshlrev_b32_e32 v72, 16, v90
	v_and_b32_e32 v73, 0xffff0000, v90
	v_lshlrev_b32_e32 v74, 16, v91
	v_and_b32_e32 v75, 0xffff0000, v91
	v_pk_mul_f32 v[72:73], v[76:77], v[72:73] op_sel_hi:[0,1]
	v_pk_mul_f32 v[74:75], v[76:77], v[74:75] op_sel_hi:[0,1]
	v_pk_mul_f32 v[84:85], v[4:5], v[72:73]
	v_pk_mul_f32 v[86:87], v[6:7], v[74:75]
	global_store_dwordx4 v41, v[84:87], s[14:15] offset:1024 nt
	s_nop 0
	v_lshlrev_b32_e32 v72, 16, v92
	v_and_b32_e32 v73, 0xffff0000, v92
	v_lshlrev_b32_e32 v74, 16, v93
	v_and_b32_e32 v75, 0xffff0000, v93
	v_pk_mul_f32 v[72:73], v[76:77], v[72:73] op_sel_hi:[0,1]
	v_pk_mul_f32 v[74:75], v[76:77], v[74:75] op_sel_hi:[0,1]
	v_pk_mul_f32 v[80:81], v[8:9], v[72:73]
	v_pk_mul_f32 v[82:83], v[10:11], v[74:75]
	global_store_dwordx4 v41, v[80:83], s[14:15] offset:2048 nt
	s_nop 0
	v_lshlrev_b32_e32 v72, 16, v94
	v_and_b32_e32 v73, 0xffff0000, v94
	v_lshlrev_b32_e32 v74, 16, v95
	v_and_b32_e32 v75, 0xffff0000, v95
	v_pk_mul_f32 v[72:73], v[76:77], v[72:73] op_sel_hi:[0,1]
	v_pk_mul_f32 v[74:75], v[76:77], v[74:75] op_sel_hi:[0,1]
	v_pk_mul_f32 v[84:85], v[12:13], v[72:73]
	v_pk_mul_f32 v[86:87], v[14:15], v[74:75]
	global_store_dwordx4 v41, v[84:87], s[14:15] offset:3072 nt
	s_nop 0
	s_waitcnt vmcnt(16)
	v_pk_add_f32 v[96:97], v[96:97], v[100:101]
	v_pk_add_f32 v[98:99], v[98:99], v[102:103]
	v_pk_add_f32 v[104:105], v[104:105], v[108:109]
	v_pk_add_f32 v[106:107], v[106:107], v[110:111]
	v_pk_add_f32 v[96:97], v[96:97], v[104:105]
	v_pk_add_f32 v[98:99], v[98:99], v[106:107]
	v_add_f32_e32 v96, v96, v97
	v_add_f32_e32 v98, v98, v99
	v_add_f32_e32 v96, v96, v98
	v_fmamk_f32 v96, v96, 0x3a800000, v22
	v_mul_f32_e32 v97, 0x4b800000, v96
	v_cmp_gt_f32_e32 vcc, s1, v96
	s_nop 1
	v_cndmask_b32_e32 v96, v96, v97, vcc
	v_rsq_f32_e32 v96, v96
	s_nop 0
	v_mul_f32_e32 v97, 0x45800000, v96
	v_cndmask_b32_e32 v100, v96, v97, vcc
	s_lshl_b32 s14, s22, 12
	s_add_u32 s14, s50, s14
	s_addc_u32 s15, s51, 0
	v_lshlrev_b32_e32 v96, 16, v112
	v_and_b32_e32 v97, 0xffff0000, v112
	v_lshlrev_b32_e32 v98, 16, v113
	v_and_b32_e32 v99, 0xffff0000, v113
	v_pk_mul_f32 v[96:97], v[100:101], v[96:97] op_sel_hi:[0,1]
	v_pk_mul_f32 v[98:99], v[100:101], v[98:99] op_sel_hi:[0,1]
	v_pk_mul_f32 v[104:105], v[0:1], v[96:97]
	v_pk_mul_f32 v[106:107], v[2:3], v[98:99]
	global_store_dwordx4 v41, v[104:107], s[14:15] nt
	v_lshlrev_b32_e32 v96, 16, v114
	v_and_b32_e32 v97, 0xffff0000, v114
	v_lshlrev_b32_e32 v98, 16, v115
	v_and_b32_e32 v99, 0xffff0000, v115
	v_pk_mul_f32 v[96:97], v[100:101], v[96:97] op_sel_hi:[0,1]
	v_pk_mul_f32 v[98:99], v[100:101], v[98:99] op_sel_hi:[0,1]
	v_pk_mul_f32 v[108:109], v[4:5], v[96:97]
	v_pk_mul_f32 v[110:111], v[6:7], v[98:99]
	global_store_dwordx4 v41, v[108:111], s[14:15] offset:1024 nt
	s_nop 0
	v_lshlrev_b32_e32 v96, 16, v116
	v_and_b32_e32 v97, 0xffff0000, v116
	v_lshlrev_b32_e32 v98, 16, v117
	v_and_b32_e32 v99, 0xffff0000, v117
	v_pk_mul_f32 v[96:97], v[100:101], v[96:97] op_sel_hi:[0,1]
	v_pk_mul_f32 v[98:99], v[100:101], v[98:99] op_sel_hi:[0,1]
	v_pk_mul_f32 v[104:105], v[8:9], v[96:97]
	v_pk_mul_f32 v[106:107], v[10:11], v[98:99]
	global_store_dwordx4 v41, v[104:107], s[14:15] offset:2048 nt
	s_nop 0
	v_lshlrev_b32_e32 v96, 16, v118
	v_and_b32_e32 v97, 0xffff0000, v118
	v_lshlrev_b32_e32 v98, 16, v119
	v_and_b32_e32 v99, 0xffff0000, v119
	v_pk_mul_f32 v[96:97], v[100:101], v[96:97] op_sel_hi:[0,1]
	v_pk_mul_f32 v[98:99], v[100:101], v[98:99] op_sel_hi:[0,1]
	v_pk_mul_f32 v[108:109], v[12:13], v[96:97]
	v_pk_mul_f32 v[110:111], v[14:15], v[98:99]
	global_store_dwordx4 v41, v[108:111], s[14:15] offset:3072 nt
	s_nop 0
	s_waitcnt vmcnt(12)
; __device__ __forceinline__ float bflo(unsigned w) { return __uint_as_float(w << 16); }
; __device__ __forceinline__ float bfhi(unsigned w) { return __uint_as_float(w & 0xffff0000u); }
; __device__ __forceinline__ float row_rstd(const float* ss, int row) {
;     const f32x4* q = (const f32x4*)(ss + (size_t)row * 16); const f32x4 s4 = (q[0] + q[1]) + (q[2] + q[3]);
;     return rsqrtf(((s4[0] + s4[1]) + (s4[2] + s4[3])) * (1.0f / D) + EPS);
; }
; __global__ void __launch_bounds__(512, 2) fwd_mega(Args a) {
;     ...
;         for (int row = gw; row < M; row += NGW) {
;             const float rs = row_rstd(ssf, row);
;             f32x4* orow = (f32x4*)(a.out + (size_t)row * D) + lane; const u32x2* xr = (const u32x2*)(XB + (size_t)row * D) + lane;
; #pragma unroll
;             for (int j = 0; j < 4; ++j) { const u32x2 w = xr[64 * j]; orow[64 * j] = (f32x4){bflo(w.x), bfhi(w.x), bflo(w.y), bfhi(w.y)} * rs * gv[j]; }
;         }
	v_pk_add_f32 v[120:121], v[120:121], v[124:125]
	v_pk_add_f32 v[122:123], v[122:123], v[126:127]
	v_pk_add_f32 v[128:129], v[128:129], v[132:133]
	v_pk_add_f32 v[130:131], v[130:131], v[134:135]
	v_pk_add_f32 v[120:121], v[120:121], v[128:129]
	v_pk_add_f32 v[122:123], v[122:123], v[130:131]
	v_add_f32_e32 v120, v120, v121
	v_add_f32_e32 v122, v122, v123
	v_add_f32_e32 v120, v120, v122
	v_fmamk_f32 v120, v120, 0x3a800000, v22
	v_mul_f32_e32 v121, 0x4b800000, v120
	v_cmp_gt_f32_e32 vcc, s1, v120
	s_nop 1
	v_cndmask_b32_e32 v120, v120, v121, vcc
	v_rsq_f32_e32 v120, v120
	s_nop 0
	v_mul_f32_e32 v121, 0x45800000, v120
	v_cndmask_b32_e32 v124, v120, v121, vcc
	s_lshl_b32 s14, s23, 12
	s_add_u32 s14, s50, s14
	s_addc_u32 s15, s51, 0
	v_lshlrev_b32_e32 v120, 16, v136
	v_and_b32_e32 v121, 0xffff0000, v136
	v_lshlrev_b32_e32 v122, 16, v137
	v_and_b32_e32 v123, 0xffff0000, v137
	v_pk_mul_f32 v[120:121], v[124:125], v[120:121] op_sel_hi:[0,1]
	v_pk_mul_f32 v[122:123], v[124:125], v[122:123] op_sel_hi:[0,1]
	v_pk_mul_f32 v[128:129], v[0:1], v[120:121]
	v_pk_mul_f32 v[130:131], v[2:3], v[122:123]
	global_store_dwordx4 v41, v[128:131], s[14:15] nt
	v_lshlrev_b32_e32 v120, 16, v138
	v_and_b32_e32 v121, 0xffff0000, v138
	v_lshlrev_b32_e32 v122, 16, v139
	v_and_b32_e32 v123, 0xffff0000, v139
	v_pk_mul_f32 v[120:121], v[124:125], v[120:121] op_sel_hi:[0,1]
	v_pk_mul_f32 v[122:123], v[124:125], v[122:123] op_sel_hi:[0,1]
	v_pk_mul_f32 v[132:133], v[4:5], v[120:121]
	v_pk_mul_f32 v[134:135], v[6:7], v[122:123]
	global_store_dwordx4 v41, v[132:135], s[14:15] offset:1024 nt
	s_nop 0
	v_lshlrev_b32_e32 v120, 16, v140
	v_and_b32_e32 v121, 0xffff0000, v140
	v_lshlrev_b32_e32 v122, 16, v141
	v_and_b32_e32 v123, 0xffff0000, v141
	v_pk_mul_f32 v[120:121], v[124:125], v[120:121] op_sel_hi:[0,1]
	v_pk_mul_f32 v[122:123], v[124:125], v[122:123] op_sel_hi:[0,1]
	v_pk_mul_f32 v[128:129], v[8:9], v[120:121]
	v_pk_mul_f32 v[130:131], v[10:11], v[122:123]
	global_store_dwordx4 v41, v[128:131], s[14:15] offset:2048 nt
	s_nop 0
	v_lshlrev_b32_e32 v120, 16, v142
	v_and_b32_e32 v121, 0xffff0000, v142
	v_lshlrev_b32_e32 v122, 16, v143
	v_and_b32_e32 v123, 0xffff0000, v143
	v_pk_mul_f32 v[120:121], v[124:125], v[120:121] op_sel_hi:[0,1]
	v_pk_mul_f32 v[122:123], v[124:125], v[122:123] op_sel_hi:[0,1]
	v_pk_mul_f32 v[132:133], v[12:13], v[120:121]
	v_pk_mul_f32 v[134:135], v[14:15], v[122:123]
	global_store_dwordx4 v41, v[132:135], s[14:15] offset:3072 nt
	s_nop 0
	s_mul_i32 s12, s16, 4
	s_add_i32 s0, s0, s12
	s_cmpk_gt_i32 s0, 0x3fff
	s_cbranch_scc0 .Lfn_loop
